# HGRN gate block: packed f32 sigmoid prep plus list-scheduled so exp/rcp are interleaved with the VALU ops (one transcendental every 3 slots)
# speedup vs baseline: 1.0081x; 1.0081x over previous
; __device__ __forceinline__ void hgrn_chain(const Params& p, LAS unsigned char* lds, int layer, int chain, int dvh) {
;     ...
;         if (c + 1 < SEQ / 64) { HG_A1(cur ^ 1); if (c + 2 < SEQ / 64) HG_LOAD(c + 2); }
.LBB0_426:
	s_xor_b32 s57, s0, 1
	s_cmpk_lg_i32 s72, 0xf840
	v_cvt_pk_bf16_f32 v34, v35, v36
	v_add_u32_e32 v36, s78, v126
	s_cselect_b64 s[70:71], -1, 0
	s_cmpk_eq_i32 s72, 0xf840
	v_cvt_pk_bf16_f32 v35, v37, v85
	ds_write_b64 v36, v[34:35]
	s_cbranch_scc1 .LBB0_442
	s_waitcnt vmcnt(0)
	s_mov_b32 s0, 0xbfb8aa3b
	s_mov_b32 s1, 0xbfb8aa3b
	s_mov_b32 s96, 1.0
	s_mov_b32 s97, 1.0
	v_lshlrev_b32_e32 v45, 16, v105
	v_lshlrev_b32_e32 v44, 16, v89
	v_lshlrev_b32_e32 v7, 16, v90
	v_lshlrev_b32_e32 v6, 16, v91
	v_pk_mul_f32 v[44:45], v[44:45], s[0:1]
	v_pk_mul_f32 v[6:7], v[6:7], s[0:1]
	v_min_f32_e32 v44, 0x42ad1f97, v44
	v_exp_f32_e32 v44, v44
	v_min_f32_e32 v45, 0x42ad1f97, v45
	v_min_f32_e32 v6, 0x42ad1f97, v6
	v_exp_f32_e32 v45, v45
	v_min_f32_e32 v7, 0x42ad1f97, v7
	v_lshlrev_b32_e32 v63, 16, v92
	v_exp_f32_e32 v6, v6
	v_lshlrev_b32_e32 v62, 16, v93
	v_pk_add_f32 v[34:35], v[44:45], s[96:97]
	v_exp_f32_e32 v7, v7
	v_pk_mul_f32 v[62:63], v[62:63], s[0:1]
	v_pk_add_f32 v[8:9], v[6:7], s[96:97]
	v_rcp_f32_e32 v43, v35
	v_lshlrev_b32_e32 v67, 16, v95
	v_lshlrev_b32_e32 v66, 16, v96
	v_rcp_f32_e32 v9, v9
	v_min_f32_e32 v62, 0x42ad1f97, v62
	v_min_f32_e32 v63, 0x42ad1f97, v63
	v_exp_f32_e32 v62, v62
	v_pk_mul_f32 v[66:67], v[66:67], s[0:1]
	v_lshlrev_b32_e32 v71, 16, v97
	v_exp_f32_e32 v63, v63
	v_lshlrev_b32_e32 v70, 16, v98
	v_min_f32_e32 v66, 0x42ad1f97, v66
	v_exp_f32_e32 v66, v66
	v_min_f32_e32 v67, 0x42ad1f97, v67
	v_pk_mul_f32 v[70:71], v[70:71], s[0:1]
	v_exp_f32_e32 v67, v67
	v_mul_f32_e32 v37, v40, v44
	v_lshlrev_b32_e32 v75, 16, v99
	v_rcp_f32_e32 v35, v34
	v_lshlrev_b32_e32 v74, 16, v100
	v_min_f32_e32 v70, 0x42ad1f97, v70
	v_exp_f32_e32 v70, v70
	v_min_f32_e32 v71, 0x42ad1f97, v71
	v_mul_f32_e32 v44, v40, v9
	v_exp_f32_e32 v71, v71
	v_pk_mul_f32 v[74:75], v[74:75], s[0:1]
	v_pk_add_f32 v[64:65], v[62:63], s[96:97]
	v_rcp_f32_e32 v8, v8
	v_pk_add_f32 v[46:47], v[38:39], v[44:45]
	v_lshlrev_b32_e32 v79, 16, v101
	v_rcp_f32_e32 v64, v64
	v_lshlrev_b32_e32 v78, 16, v102
	v_min_f32_e32 v74, 0x42ad1f97, v74
	v_rcp_f32_e32 v65, v65
	v_min_f32_e32 v75, 0x42ad1f97, v75
	v_pk_mul_f32 v[44:45], v[38:39], v[44:45]
	v_exp_f32_e32 v74, v74
	v_pk_mul_f32 v[78:79], v[78:79], s[0:1]
	v_pk_add_f32 v[68:69], v[66:67], s[96:97]
	v_exp_f32_e32 v75, v75
	v_fma_f32 v42, v40, v35, v38
	v_mov_b32_e32 v47, v45
	v_rcp_f32_e32 v68, v68
	v_lshlrev_b32_e32 v83, 16, v103
	v_lshlrev_b32_e32 v82, 16, v104
	v_rcp_f32_e32 v69, v69
	v_min_f32_e32 v78, 0x42ad1f97, v78
	v_min_f32_e32 v79, 0x42ad1f97, v79
	v_exp_f32_e32 v78, v78
	v_pk_mul_f32 v[44:45], v[46:47], v[42:43]
	v_pk_mul_f32 v[82:83], v[82:83], s[0:1]
	v_exp_f32_e32 v79, v79
	v_pk_add_f32 v[72:73], v[70:71], s[96:97]
	v_fma_f32 v36, v40, v8, v38
	v_rcp_f32_e32 v72, v72
	v_mov_b32_e32 v34, v44
	v_min_f32_e32 v82, 0x42ad1f97, v82
	v_rcp_f32_e32 v73, v73
	v_min_f32_e32 v83, 0x42ad1f97, v83
	v_pk_fma_f32 v[56:57], v[40:41], v[64:65], v[38:39] op_sel:[0,1,0] op_sel_hi:[0,0,0]
	v_exp_f32_e32 v82, v82
	v_pk_mul_f32 v[46:47], v[34:35], v[36:37]
	v_pk_add_f32 v[76:77], v[74:75], s[96:97]
	v_exp_f32_e32 v83, v83
	v_mul_f32_e32 v106, v46, v56
	v_pk_fma_f32 v[58:59], v[40:41], v[68:69], v[38:39] op_sel:[0,1,0] op_sel_hi:[0,0,0]
	v_rcp_f32_e32 v76, v76
	v_mul_f32_e32 v107, v106, v57
	v_pk_add_f32 v[80:81], v[78:79], s[96:97]
	v_rcp_f32_e32 v77, v77
	v_mul_f32_e32 v108, v107, v58
	v_pk_fma_f32 v[60:61], v[40:41], v[72:73], v[38:39] op_sel:[0,1,0] op_sel_hi:[0,0,0]
	v_rcp_f32_e32 v80, v80
	v_mul_f32_e32 v109, v108, v59
	v_pk_add_f32 v[84:85], v[82:83], s[96:97]
	v_rcp_f32_e32 v81, v81
	v_mul_f32_e32 v110, v109, v60
	v_pk_fma_f32 v[112:113], v[40:41], v[76:77], v[38:39] op_sel:[0,1,0] op_sel_hi:[0,0,0]
	v_rcp_f32_e32 v84, v84
	v_mul_f32_e32 v111, v110, v61
	v_mul_f32_e32 v112, v111, v112
	v_rcp_f32_e32 v85, v85
	v_pk_fma_f32 v[114:115], v[40:41], v[80:81], v[38:39] op_sel:[0,1,0] op_sel_hi:[0,0,0]
	v_mul_f32_e32 v113, v112, v113
	v_mul_f32_e32 v114, v113, v114
	v_pk_fma_f32 v[116:117], v[40:41], v[84:85], v[38:39] op_sel:[0,1,0] op_sel_hi:[0,0,0]
	v_mul_f32_e32 v115, v114, v115
	v_mul_f32_e32 v116, v115, v116
	v_fma_f32 v118, v40, v43, v38
	v_mul_f32_e32 v117, v116, v117
	v_mul_f32_e32 v118, v117, v118
	v_lshl_add_u32 v34, s57, 11, v94
	ds_write_b32 v34, v118
	s_waitcnt vmcnt(0)
	s_cmp_gt_u32 s56, 29
	v_perm_b32 v152, v194, v195, s87
	v_perm_b32 v151, v196, v197, s87
	v_perm_b32 v150, v198, v199, s87
	v_perm_b32 v149, v200, v201, s87
	v_perm_b32 v148, v202, v203, s87
	v_perm_b32 v147, v204, v205, s87
	v_perm_b32 v146, v206, v207, s87
	v_perm_b32 v145, v208, v209, s87
	v_mov_b64_e32 v[2:3], v[210:211]
	v_mov_b64_e32 v[4:5], v[212:213]
	s_cbranch_scc1 .LBB0_441
	v_cndmask_b32_e64 v34, 0, 1, s[8:9]
	s_mov_b64 s[96:97], -1
	v_cmp_ne_u32_e64 s[0:1], 1, v34
	s_andn2_b64 vcc, exec, s[8:9]
	v_add_u32_e32 v34, s72, v138
	s_cbranch_vccnz .LBB0_432
	v_add_u32_e32 v36, s72, v138
	s_add_i32 s59, s56, 2
	v_lshl_add_u32 v35, s59, 6, v87
	s_cbranch_execz .LBB0_433
